# NSA fastp tile loop: far tiles both halves software-pipelined (V frags prefetched, exp of half 0 under QK of half 1); near tiles: LUT reads hoisted, masks without SALU chain
# speedup vs baseline: 1.0021x; 1.0021x over previous
; __device__ __forceinline__ void pv_half_tr(const LAS unsigned char* vb, const unsigned (&pw)[8], const TrAddr& ta, int hf, f32x16& o0, f32x16& o1, f32x16& os, bf16x8 ones) {
; __device__ __forceinline__ void nsa_unit(const Params& p, LAS unsigned char* lds, int b, int hkv, int i, int tid, int lane, int wave) {
;     ...
;         for (int it = 0; it < nt; ++it) {
;             const int j = msb64(crem); crem &= ~(1ull << j);
;             const int ahead = nt - 1 - it;
;             RING_WAIT(ahead);
;             if (it + 3 < nt) { const int ji = msb64(irem); irem &= ~(1ull << ji); rg.issue(Kb + (size_t)ji * 64 * ZW, ZW, Vb + (size_t)ji * 64 * ZW, ZW, (it + 3) & 3); }
;                 if ((wm >> j) & 1ull) {
;                     const LAS unsigned char* stg = lds + (it & 3) * STG_BYTES;
;                     const int dj = i - j;
;                     const bool lsel = (lm >> j) & 1ull;
;                     const int db = 64 * dj + tq - 4 * hi;
; #pragma unroll
;                     for (int hf = 0; hf < 2; ++hf) {
;                         f32x16 s; unsigned pw[8];
;                         if (dj <= 2) {
;                             qk_half(stg, qf, col, hi, hf, s, -mref);
;                             const LAS float* l2p = (const LAS float*)(lds + LUT2_OFF) + head * 260 + db + 5;
; #pragma unroll
;                             for (int r = 0; r < 16; ++r) { const float x = s[r] + l2p[63 - KKOF(hf, r)]; s[r] = (lsel && KKOF(hf, r) <= db) ? ex2(x) : 0.f; }
; #pragma unroll
;                             for (int r = 0; r < 8; ++r) pw[r] = pk2(s[2 * r], s[2 * r + 1]);
;                         } else if (dj == 8) {
;                             qk_half_c(stg, qf, col, hi, hf, s, cfar);
; #pragma unroll
;                             for (int r = 0; r < 16; ++r) { const int d_ = db - KKOF(hf, r); s[r] = (lsel && d_ < dmax) ? ex2(s[r]) : 0.f; }
; #pragma unroll
;                             for (int r = 0; r < 8; ++r) pw[r] = pk2(s[2 * r], s[2 * r + 1]);
;                         } else {
;                             qk_half_c(stg, qf, col, hi, hf, s, cfar);
; #pragma unroll
;                             for (int r = 0; r < 8; ++r) { const unsigned w_ = pk2(ex2(s[2 * r]), ex2(s[2 * r + 1])); pw[r] = lsel ? w_ : 0u; }
;                         }
;                         pv_half_tr(stg + 8192, pw, tra, hf, o0, o1, os, ones);
;                     }
.LBB0_563:
	s_flbit_i32_b64 s0, s[34:35]
	s_xor_b32 s4, s0, 63
	s_lshl_b64 s[2:3], 1, s4
	s_and_b64 s[10:11], s[2:3], s[48:49]
	s_cmp_eq_u64 s[10:11], 0
	s_cbranch_scc1 .LBB0_554
	s_and_b32 s0, s79, 0xc000
	s_add_i32 s0, s0, 0
	v_add_u32_e32 v12, s0, v203
	v_and_b32_e32 v5, s3, v214
	v_and_b32_e32 v4, s2, v215
	v_add_u32_e32 v125, v12, v204
	v_add_u32_e32 v127, v12, v206
	v_cmp_eq_u64_e64 s[22:23], 0, v[4:5]
	v_add_u32_e32 v126, v12, v205
	ds_read_b128 v[4:7], v125
	ds_read_b128 v[8:11], v126
	v_add_u32_e32 v128, v12, v207
	ds_read_b128 v[12:15], v127
	ds_read_b128 v[116:119], v128
	s_sub_i32 s4, s67, s4
	s_cmp_gt_i32 s4, 2
	s_cselect_b64 s[12:13], -1, 0
	s_cmp_lg_u32 s4, 8
	v_lshl_add_u32 v2, s4, 6, v212
	s_cselect_b64 s[10:11], -1, 0
	s_mov_b64 s[14:15], -1
	s_and_b64 vcc, exec, s[12:13]
	s_cbranch_vccz .LBB0_570
	s_and_b64 vcc, exec, s[10:11]
	s_cbranch_vccz .LBB0_567
	v_add3_u32 v248, s0, v208, v209
	v_add3_u32 v249, s0, v208, v210
	ds_read_b64_tr_b16 v[236:237], v248 offset:8192
	ds_read_b64_tr_b16 v[238:239], v248 offset:9216
	ds_read_b64_tr_b16 v[240:241], v249 offset:8192
	ds_read_b64_tr_b16 v[242:243], v249 offset:9216
	ds_read_b64_tr_b16 v[244:245], v248 offset:10240
	ds_read_b64_tr_b16 v[246:247], v248 offset:11264
	s_waitcnt lgkmcnt(9)
	v_mfma_f32_32x32x16_bf16 v[100:115], v[4:7], v[148:151], v[68:83]
	ds_read_b128 v[4:7], v125 offset:4096
	s_waitcnt lgkmcnt(9)
	v_mfma_f32_32x32x16_bf16 v[100:115], v[8:11], v[152:155], v[100:115]
	ds_read_b128 v[8:11], v126 offset:4096
	s_waitcnt lgkmcnt(9)
	v_mfma_f32_32x32x16_bf16 v[100:115], v[12:15], v[156:159], v[100:115]
	ds_read_b128 v[12:15], v127 offset:4096
	s_waitcnt lgkmcnt(9)
	v_mfma_f32_32x32x16_bf16 v[100:115], v[116:119], v[160:163], v[100:115]
	ds_read_b128 v[116:119], v128 offset:4096
	v_mov_b32_e32 v252, s88
	v_mov_b32_e32 v253, s88
	v_mov_b32_e32 v254, s88
	v_mov_b32_e32 v255, s88
	s_waitcnt lgkmcnt(3)
	v_mfma_f32_32x32x16_bf16 v[220:235], v[4:7], v[148:151], v[68:83]
	s_waitcnt lgkmcnt(2)
	v_mfma_f32_32x32x16_bf16 v[220:235], v[8:11], v[152:155], v[220:235]
	s_nop 2
	v_exp_f32_e32 v100, v100
	v_exp_f32_e32 v101, v101
	v_exp_f32_e32 v102, v102
	v_exp_f32_e32 v103, v103
	s_waitcnt lgkmcnt(1)
	v_mfma_f32_32x32x16_bf16 v[220:235], v[12:15], v[156:159], v[220:235]
	v_exp_f32_e32 v104, v104
	v_exp_f32_e32 v105, v105
	v_exp_f32_e32 v106, v106
	v_exp_f32_e32 v107, v107
	s_waitcnt lgkmcnt(0)
	v_mfma_f32_32x32x16_bf16 v[220:235], v[116:119], v[160:163], v[220:235]
	ds_read_b64_tr_b16 v[4:5], v248 offset:12288
	ds_read_b64_tr_b16 v[6:7], v248 offset:13312
	ds_read_b64_tr_b16 v[8:9], v249 offset:12288
	ds_read_b64_tr_b16 v[10:11], v249 offset:13312
	ds_read_b64_tr_b16 v[12:13], v248 offset:14336
	ds_read_b64_tr_b16 v[14:15], v248 offset:15360
	ds_read_b64_tr_b16 v[116:117], v249 offset:14336
	ds_read_b64_tr_b16 v[118:119], v249 offset:15360
	v_exp_f32_e32 v108, v108
	v_exp_f32_e32 v109, v109
	v_exp_f32_e32 v110, v110
	v_exp_f32_e32 v111, v111
	v_exp_f32_e32 v112, v112
	v_exp_f32_e32 v113, v113
	v_exp_f32_e32 v114, v114
	v_exp_f32_e32 v115, v115
	v_cvt_pk_bf16_f32 v100, v100, v101
	v_cvt_pk_bf16_f32 v101, v102, v103
	v_cvt_pk_bf16_f32 v102, v104, v105
	v_cvt_pk_bf16_f32 v103, v106, v107
	v_cvt_pk_bf16_f32 v104, v108, v109
	v_cvt_pk_bf16_f32 v105, v110, v111
	v_cvt_pk_bf16_f32 v106, v112, v113
	v_cvt_pk_bf16_f32 v107, v114, v115
	ds_read_b64_tr_b16 v[108:109], v249 offset:10240
	ds_read_b64_tr_b16 v[110:111], v249 offset:11264
	v_cndmask_b32_e64 v100, v100, 0, s[22:23]
	v_cndmask_b32_e64 v101, v101, 0, s[22:23]
	v_cndmask_b32_e64 v102, v102, 0, s[22:23]
	v_cndmask_b32_e64 v103, v103, 0, s[22:23]
	v_cndmask_b32_e64 v104, v104, 0, s[22:23]
	v_cndmask_b32_e64 v105, v105, 0, s[22:23]
	v_cndmask_b32_e64 v106, v106, 0, s[22:23]
	v_cndmask_b32_e64 v107, v107, 0, s[22:23]
	v_mfma_f32_32x32x16_bf16 v[36:51], v[236:239], v[100:103], v[36:51]
	v_exp_f32_e32 v220, v220
	v_exp_f32_e32 v221, v221
	v_exp_f32_e32 v222, v222
	v_exp_f32_e32 v223, v223
	v_mfma_f32_32x32x16_bf16 v[20:35], v[240:243], v[100:103], v[20:35]
	v_exp_f32_e32 v224, v224
	v_exp_f32_e32 v225, v225
	v_exp_f32_e32 v226, v226
	v_exp_f32_e32 v227, v227
	v_mfma_f32_32x32x16_bf16 v[52:67], v[252:255], v[100:103], v[52:67]
	v_exp_f32_e32 v228, v228
	v_exp_f32_e32 v229, v229
	v_exp_f32_e32 v230, v230
	v_exp_f32_e32 v231, v231
	v_mfma_f32_32x32x16_bf16 v[36:51], v[244:247], v[104:107], v[36:51]
	v_exp_f32_e32 v232, v232
	v_exp_f32_e32 v233, v233
	v_exp_f32_e32 v234, v234
	v_exp_f32_e32 v235, v235
	s_waitcnt lgkmcnt(0)
	v_mfma_f32_32x32x16_bf16 v[20:35], v[108:111], v[104:107], v[20:35]
	v_cvt_pk_bf16_f32 v220, v220, v221
	v_cvt_pk_bf16_f32 v221, v222, v223
	v_cvt_pk_bf16_f32 v222, v224, v225
	v_cvt_pk_bf16_f32 v223, v226, v227
	v_mfma_f32_32x32x16_bf16 v[52:67], v[252:255], v[104:107], v[52:67]
	v_cvt_pk_bf16_f32 v224, v228, v229
	v_cvt_pk_bf16_f32 v225, v230, v231
	v_cvt_pk_bf16_f32 v226, v232, v233
	v_cvt_pk_bf16_f32 v227, v234, v235
	v_cndmask_b32_e64 v220, v220, 0, s[22:23]
	v_cndmask_b32_e64 v221, v221, 0, s[22:23]
	v_cndmask_b32_e64 v222, v222, 0, s[22:23]
	v_cndmask_b32_e64 v223, v223, 0, s[22:23]
	v_cndmask_b32_e64 v224, v224, 0, s[22:23]
	v_cndmask_b32_e64 v225, v225, 0, s[22:23]
	v_cndmask_b32_e64 v226, v226, 0, s[22:23]
	v_cndmask_b32_e64 v227, v227, 0, s[22:23]
	v_mfma_f32_32x32x16_bf16 v[36:51], v[4:7], v[220:223], v[36:51]
	v_mfma_f32_32x32x16_bf16 v[20:35], v[8:11], v[220:223], v[20:35]
	v_mfma_f32_32x32x16_bf16 v[52:67], v[252:255], v[220:223], v[52:67]
	v_mfma_f32_32x32x16_bf16 v[36:51], v[12:15], v[224:227], v[36:51]
	v_mfma_f32_32x32x16_bf16 v[20:35], v[116:119], v[224:227], v[20:35]
	v_mfma_f32_32x32x16_bf16 v[52:67], v[252:255], v[224:227], v[52:67]
	s_branch .LBB0_554

; #define LAS __attribute__((address_space(3)))
; __device__ __forceinline__ unsigned pk2(float lo, float hi) { f32x2_t v = {lo, hi}; bf16x2_t b = __builtin_convertvector(v, bf16x2_t); return __builtin_bit_cast(unsigned, b); }
; __device__ __forceinline__ float ex2(float x) { return __builtin_amdgcn_exp2f(x); }
; #define MFMA32(a, b, c) __builtin_amdgcn_mfma_f32_32x32x16_bf16((a), (b), (c), 0, 0, 0)
; __device__ __forceinline__ void qk_half_c(const LAS unsigned char* kb, const bf16x8 (&qf)[4], int col, int hi, int hf, f32x16& s, const f32x16& c) {
;     const LAS unsigned char* k0 = kb + (32 * hf + col) * 128; const int k7 = col & 7;
;     bf16x8 a[4];
; #pragma unroll
;     for (int d0 = 0; d0 < 4; ++d0) a[d0] = *(const LAS bf16x8*)(k0 + (((2 * d0 + hi) ^ k7) << 4));
;     asm volatile("" ::: "memory");
;     s = MFMA32(a[0], qf[0], c);
; #pragma unroll
;     for (int d0 = 1; d0 < 4; ++d0) s = MFMA32(a[d0], qf[d0], s);
; }
; __device__ __forceinline__ void nsa_unit(const Params& p, LAS unsigned char* lds, int b, int hkv, int i, int tid, int lane, int wave) {
;     ...
;                         if (dj <= 2) {
;                             qk_half(stg, qf, col, hi, hf, s, -mref);
;                             const LAS float* l2p = (const LAS float*)(lds + LUT2_OFF) + head * 260 + db + 5;
; #pragma unroll
;                             for (int r = 0; r < 16; ++r) { const float x = s[r] + l2p[63 - KKOF(hf, r)]; s[r] = (lsel && KKOF(hf, r) <= db) ? ex2(x) : 0.f; }
; #pragma unroll
;                             for (int r = 0; r < 8; ++r) pw[r] = pk2(s[2 * r], s[2 * r + 1]);
.LBB0_570:
	s_andn2_b64 vcc, exec, s[14:15]
	v_lshl_add_u32 v16, v2, 2, v213
	s_cbranch_vccnz .LBB0_572
	ds_read2_b32 v[220:221], v16 offset0:67 offset1:68
	ds_read2_b32 v[222:223], v16 offset0:65 offset1:66
	ds_read2_b32 v[224:225], v16 offset0:59 offset1:60
	ds_read2_b32 v[226:227], v16 offset0:57 offset1:58
	ds_read2_b32 v[228:229], v16 offset0:51 offset1:52
	ds_read2_b32 v[230:231], v16 offset0:49 offset1:50
	ds_read2_b32 v[232:233], v16 offset0:43 offset1:44
	ds_read2_b32 v[234:235], v16 offset0:41 offset1:42
	v_cndmask_b32_e64 v236, v2, -1, s[22:23]
	s_waitcnt lgkmcnt(11)
	v_mfma_f32_32x32x16_bf16 v[100:115], v[4:7], v[148:151], v[84:99]
	s_waitcnt lgkmcnt(10)
	v_mfma_f32_32x32x16_bf16 v[100:115], v[8:11], v[152:155], v[100:115]
	s_waitcnt lgkmcnt(9)
	v_mfma_f32_32x32x16_bf16 v[100:115], v[12:15], v[156:159], v[100:115]
	s_waitcnt lgkmcnt(8)
	v_mfma_f32_32x32x16_bf16 v[100:115], v[116:119], v[160:163], v[100:115]
	s_waitcnt lgkmcnt(0)
	s_nop 10
	v_add_f32_e32 v100, v100, v221
	v_exp_f32_e32 v100, v100
	v_cmp_gt_i32_e32 vcc, 0, v236
	v_add_f32_e32 v101, v101, v220
	v_exp_f32_e32 v101, v101
	v_cndmask_b32_e64 v100, v100, 0, vcc
	v_cmp_gt_i32_e32 vcc, 1, v236
	v_add_f32_e32 v102, v102, v223
	v_exp_f32_e32 v102, v102
	v_cndmask_b32_e64 v101, v101, 0, vcc
	v_cmp_gt_i32_e32 vcc, 2, v236
	v_add_f32_e32 v103, v103, v222
	v_exp_f32_e32 v103, v103
	v_cndmask_b32_e64 v102, v102, 0, vcc
	v_cmp_gt_i32_e32 vcc, 3, v236
	v_add_f32_e32 v104, v104, v225
	v_exp_f32_e32 v104, v104
	v_cndmask_b32_e64 v103, v103, 0, vcc
	v_cmp_gt_i32_e32 vcc, 8, v236
	v_add_f32_e32 v105, v105, v224
	v_exp_f32_e32 v105, v105
	v_cndmask_b32_e64 v104, v104, 0, vcc
	v_cmp_gt_i32_e32 vcc, 9, v236
	v_add_f32_e32 v106, v106, v227
	v_exp_f32_e32 v106, v106
	v_cndmask_b32_e64 v105, v105, 0, vcc
	v_cmp_gt_i32_e32 vcc, 10, v236
	v_add_f32_e32 v107, v107, v226
	v_exp_f32_e32 v107, v107
	v_cndmask_b32_e64 v106, v106, 0, vcc
	v_cmp_gt_i32_e32 vcc, 11, v236
	v_add_f32_e32 v108, v108, v229
	v_exp_f32_e32 v108, v108
	v_cndmask_b32_e64 v107, v107, 0, vcc
	v_cmp_gt_i32_e32 vcc, 16, v236
	v_add_f32_e32 v109, v109, v228
	v_exp_f32_e32 v109, v109
	v_cndmask_b32_e64 v108, v108, 0, vcc
	v_cmp_gt_i32_e32 vcc, 17, v236
	v_add_f32_e32 v110, v110, v231
	v_exp_f32_e32 v110, v110
	v_cndmask_b32_e64 v109, v109, 0, vcc
	v_cmp_gt_i32_e32 vcc, 18, v236
	v_add_f32_e32 v111, v111, v230
	v_exp_f32_e32 v111, v111
	v_cndmask_b32_e64 v110, v110, 0, vcc
	v_cmp_gt_i32_e32 vcc, 19, v236
	v_add_f32_e32 v112, v112, v233
	v_exp_f32_e32 v112, v112
	v_cndmask_b32_e64 v111, v111, 0, vcc
	v_cmp_gt_i32_e32 vcc, 24, v236
	v_add_f32_e32 v113, v113, v232
	v_exp_f32_e32 v113, v113
	v_cndmask_b32_e64 v112, v112, 0, vcc
	v_cmp_gt_i32_e32 vcc, 25, v236
	v_add_f32_e32 v114, v114, v235
	v_exp_f32_e32 v114, v114
	v_cndmask_b32_e64 v113, v113, 0, vcc
	v_cmp_gt_i32_e32 vcc, 26, v236
	v_add_f32_e32 v115, v115, v234
	v_exp_f32_e32 v115, v115
	v_cndmask_b32_e64 v114, v114, 0, vcc
	v_cmp_gt_i32_e32 vcc, 27, v236
	s_nop 1
	v_cndmask_b32_e64 v115, v115, 0, vcc
	v_cvt_pk_bf16_f32 v100, v100, v101
	v_cvt_pk_bf16_f32 v101, v102, v103
	v_cvt_pk_bf16_f32 v102, v104, v105
	v_cvt_pk_bf16_f32 v103, v106, v107
	v_cvt_pk_bf16_f32 v104, v108, v109
	v_cvt_pk_bf16_f32 v105, v110, v111
	v_cvt_pk_bf16_f32 v106, v112, v113
	v_cvt_pk_bf16_f32 v107, v114, v115
; __device__ __forceinline__ void pv_half_tr(const LAS unsigned char* vb, const unsigned (&pw)[8], const TrAddr& ta, int hf, f32x16& o0, f32x16& o1, f32x16& os, bf16x8 ones) {
;     const LAS unsigned char* v0 = vb + ta.base0;
;     v2u a0[2], a1[2], b0[2], b1[2];
; #pragma unroll
;     for (int s2 = 0; s2 < 2; ++s2) { const int ro = (2 * hf + s2) * 2048;
;         a0[s2] = vtr8(v0 + ro + ta.ch0); a1[s2] = vtr8(v0 + ro + 1024 + ta.ch0); b0[s2] = vtr8(v0 + ro + ta.ch1); b1[s2] = vtr8(v0 + ro + 1024 + ta.ch1); }
; #pragma unroll
;     for (int s2 = 0; s2 < 2; ++s2) {
;         const v4u pu = {pw[4 * s2], pw[4 * s2 + 1], pw[4 * s2 + 2], pw[4 * s2 + 3]};
;         const bf16x8 pf = __builtin_bit_cast(bf16x8, pu);
;         const v4u au = {a0[s2].x, a0[s2].y, a1[s2].x, a1[s2].y}, bu = {b0[s2].x, b0[s2].y, b1[s2].x, b1[s2].y};
; __device__ __forceinline__ void nsa_unit(const Params& p, LAS unsigned char* lds, int b, int hkv, int i, int tid, int lane, int wave) {
;     ...
; #pragma unroll
;                     for (int hf = 0; hf < 2; ++hf) {
;                         f32x16 s; unsigned pw[8];
;                         if (dj <= 2) {
;                             qk_half(stg, qf, col, hi, hf, s, -mref);
;                             const LAS float* l2p = (const LAS float*)(lds + LUT2_OFF) + head * 260 + db + 5;
; #pragma unroll
;                             for (int r = 0; r < 16; ++r) { const float x = s[r] + l2p[63 - KKOF(hf, r)]; s[r] = (lsel && KKOF(hf, r) <= db) ? ex2(x) : 0.f; }
; #pragma unroll
;                             for (int r = 0; r < 8; ++r) pw[r] = pk2(s[2 * r], s[2 * r + 1]);
;                         } else if (dj == 8) {
;                             qk_half_c(stg, qf, col, hi, hf, s, cfar);
; #pragma unroll
;                             for (int r = 0; r < 16; ++r) { const int d_ = db - KKOF(hf, r); s[r] = (lsel && d_ < dmax) ? ex2(s[r]) : 0.f; }
; #pragma unroll
;                             for (int r = 0; r < 8; ++r) pw[r] = pk2(s[2 * r], s[2 * r + 1]);
;                         } else {
;                             qk_half_c(stg, qf, col, hi, hf, s, cfar);
; #pragma unroll
;                             for (int r = 0; r < 8; ++r) { const unsigned w_ = pk2(ex2(s[2 * r]), ex2(s[2 * r + 1])); pw[r] = lsel ? w_ : 0u; }
;                         }
;                         pv_half_tr(stg + 8192, pw, tra, hf, o0, o1, os, ones);
;                     }
.LBB0_572:
	s_waitcnt lgkmcnt(2)
	v_add_u32_e32 v8, s0, v208
	v_add_u32_e32 v124, v8, v209
	ds_read_b64_tr_b16 v[4:5], v124 offset:8192
	ds_read_b64_tr_b16 v[6:7], v124 offset:9216
	s_mov_b32 s89, s88
	s_mov_b32 s90, s88
	s_mov_b32 s91, s88
	v_add_u32_e32 v17, v8, v210
	s_waitcnt lgkmcnt(0)
	v_mfma_f32_32x32x16_bf16 v[36:51], v[4:7], v[100:103], v[36:51]
	v_mov_b64_e32 v[4:5], s[88:89]
	v_mov_b64_e32 v[6:7], s[90:91]
	ds_read_b64_tr_b16 v[8:9], v17 offset:8192
	ds_read_b64_tr_b16 v[10:11], v17 offset:9216
	ds_read_b64_tr_b16 v[12:13], v124 offset:10240
	ds_read_b64_tr_b16 v[14:15], v124 offset:11264
	ds_read_b64_tr_b16 v[108:109], v17 offset:10240
	ds_read_b64_tr_b16 v[110:111], v17 offset:11264
	s_mov_b64 s[14:15], -1
	s_andn2_b64 vcc, exec, s[12:13]
	s_waitcnt lgkmcnt(4)
	v_mfma_f32_32x32x16_bf16 v[20:35], v[8:11], v[100:103], v[20:35]
	v_mfma_f32_32x32x16_bf16 v[52:67], v[4:7], v[100:103], v[52:67]
	s_waitcnt lgkmcnt(2)
	v_mfma_f32_32x32x16_bf16 v[36:51], v[12:15], v[104:107], v[36:51]
	s_waitcnt lgkmcnt(0)
	v_mfma_f32_32x32x16_bf16 v[20:35], v[108:111], v[104:107], v[20:35]
	v_mfma_f32_32x32x16_bf16 v[52:67], v[4:7], v[104:107], v[52:67]
	ds_read_b128 v[4:7], v125 offset:4096
	ds_read_b128 v[8:11], v126 offset:4096
	ds_read_b128 v[12:15], v127 offset:4096
	ds_read_b128 v[116:119], v128 offset:4096
	s_cbranch_vccnz .LBB0_578
	s_andn2_b64 vcc, exec, s[10:11]
	s_mov_b64 s[10:11], -1
	s_cbranch_vccnz .LBB0_575
.LBB0_575:
	s_andn2_b64 vcc, exec, s[10:11]
	s_cbranch_vccnz .LBB0_577
	s_waitcnt lgkmcnt(3)
	v_mfma_f32_32x32x16_bf16 v[100:115], v[4:7], v[148:151], v[68:83]
	v_cmp_gt_i32_e32 vcc, s57, v2
	s_waitcnt lgkmcnt(2)
	v_mfma_f32_32x32x16_bf16 v[100:115], v[8:11], v[152:155], v[100:115]
	s_waitcnt lgkmcnt(1)
	v_mfma_f32_32x32x16_bf16 v[100:115], v[12:15], v[156:159], v[100:115]
	s_waitcnt lgkmcnt(0)
	v_mfma_f32_32x32x16_bf16 v[100:115], v[116:119], v[160:163], v[100:115]
	s_nop 11
	v_exp_f32_e32 v100, v100
	v_exp_f32_e32 v101, v101
	v_exp_f32_e32 v102, v102
	v_exp_f32_e32 v103, v103
	v_exp_f32_e32 v104, v104
	v_cndmask_b32_e32 v100, 0, v100, vcc
	v_cmp_gt_i32_e32 vcc, s58, v2
	v_exp_f32_e32 v105, v105
	v_exp_f32_e32 v106, v106
	v_cndmask_b32_e32 v101, 0, v101, vcc
	v_cmp_gt_i32_e32 vcc, s59, v2
	v_exp_f32_e32 v107, v107
	v_exp_f32_e32 v108, v108
	v_cndmask_b32_e32 v102, 0, v102, vcc
	v_cmp_gt_i32_e32 vcc, s60, v2
	v_cndmask_b32_e64 v100, v100, 0, s[22:23]
	v_cndmask_b32_e64 v101, v101, 0, s[22:23]
	v_cndmask_b32_e32 v103, 0, v103, vcc
	v_cmp_gt_i32_e32 vcc, s61, v2
	v_cndmask_b32_e64 v102, v102, 0, s[22:23]
	v_cndmask_b32_e64 v103, v103, 0, s[22:23]
	v_cndmask_b32_e32 v104, 0, v104, vcc
	v_cmp_gt_i32_e32 vcc, s62, v2
	v_cndmask_b32_e64 v125, v104, 0, s[22:23]
	v_exp_f32_e32 v104, v109
	v_cndmask_b32_e32 v105, 0, v105, vcc
	v_cmp_gt_i32_e32 vcc, s63, v2
	v_cndmask_b32_e64 v126, v105, 0, s[22:23]
	s_nop 0
	v_cndmask_b32_e32 v106, 0, v106, vcc
	v_cmp_gt_i32_e32 vcc, s66, v2
	v_cndmask_b32_e64 v127, v106, 0, s[22:23]
	v_cvt_pk_bf16_f32 v106, v125, v126
	v_cndmask_b32_e32 v107, 0, v107, vcc
	v_cmp_gt_i32_e32 vcc, s70, v2
	v_cndmask_b32_e64 v107, v107, 0, s[22:23]
	v_cvt_pk_bf16_f32 v107, v127, v107
	v_cndmask_b32_e32 v105, 0, v108, vcc
	v_cmp_gt_i32_e32 vcc, s71, v2
	v_cndmask_b32_e64 v108, v105, 0, s[22:23]
	v_exp_f32_e32 v105, v110
	v_cndmask_b32_e32 v104, 0, v104, vcc
	v_cndmask_b32_e64 v109, v104, 0, s[22:23]
	v_exp_f32_e32 v104, v111
	v_cmp_gt_i32_e32 vcc, s72, v2
	s_nop 1
	v_cndmask_b32_e32 v105, 0, v105, vcc
	v_cmp_gt_i32_e32 vcc, s73, v2
	v_cndmask_b32_e64 v110, v105, 0, s[22:23]
	v_exp_f32_e32 v105, v112
	v_cndmask_b32_e32 v104, 0, v104, vcc
	v_cndmask_b32_e64 v111, v104, 0, s[22:23]
	v_exp_f32_e32 v104, v113
	v_cmp_gt_i32_e32 vcc, s74, v2
	s_nop 1
	v_cndmask_b32_e32 v105, 0, v105, vcc
	v_cmp_gt_i32_e32 vcc, s75, v2
	v_cndmask_b32_e64 v112, v105, 0, s[22:23]
	v_exp_f32_e32 v105, v114
	v_cndmask_b32_e32 v104, 0, v104, vcc
	v_cndmask_b32_e64 v113, v104, 0, s[22:23]
	v_exp_f32_e32 v104, v115
	v_cmp_gt_i32_e32 vcc, s76, v2
	s_nop 1
	v_cndmask_b32_e32 v105, 0, v105, vcc
	v_cmp_gt_i32_e32 vcc, s77, v2
	v_cndmask_b32_e64 v114, v105, 0, s[22:23]
	v_cvt_pk_bf16_f32 v105, v102, v103
	v_cndmask_b32_e32 v104, 0, v104, vcc
	v_cndmask_b32_e64 v115, v104, 0, s[22:23]
	v_cvt_pk_bf16_f32 v104, v100, v101
	v_cvt_pk_bf16_f32 v100, v108, v109
	v_cvt_pk_bf16_f32 v101, v110, v111
	v_cvt_pk_bf16_f32 v102, v112, v113
	v_cvt_pk_bf16_f32 v103, v114, v115

; #define LAS __attribute__((address_space(3)))
; __device__ __forceinline__ unsigned pk2(float lo, float hi) { f32x2_t v = {lo, hi}; bf16x2_t b = __builtin_convertvector(v, bf16x2_t); return __builtin_bit_cast(unsigned, b); }
; __device__ __forceinline__ float ex2(float x) { return __builtin_amdgcn_exp2f(x); }
; #define MFMA32(a, b, c) __builtin_amdgcn_mfma_f32_32x32x16_bf16((a), (b), (c), 0, 0, 0)
; __device__ __forceinline__ void qk_half_c(const LAS unsigned char* kb, const bf16x8 (&qf)[4], int col, int hi, int hf, f32x16& s, const f32x16& c) {
;     const LAS unsigned char* k0 = kb + (32 * hf + col) * 128; const int k7 = col & 7;
;     bf16x8 a[4];
; #pragma unroll
;     for (int d0 = 0; d0 < 4; ++d0) a[d0] = *(const LAS bf16x8*)(k0 + (((2 * d0 + hi) ^ k7) << 4));
;     asm volatile("" ::: "memory");
;     s = MFMA32(a[0], qf[0], c);
; #pragma unroll
;     for (int d0 = 1; d0 < 4; ++d0) s = MFMA32(a[d0], qf[d0], s);
; }
; __device__ __forceinline__ void nsa_unit(const Params& p, LAS unsigned char* lds, int b, int hkv, int i, int tid, int lane, int wave) {
;     ...
;                         if (dj <= 2) {
;                             qk_half(stg, qf, col, hi, hf, s, -mref);
;                             const LAS float* l2p = (const LAS float*)(lds + LUT2_OFF) + head * 260 + db + 5;
; #pragma unroll
;                             for (int r = 0; r < 16; ++r) { const float x = s[r] + l2p[63 - KKOF(hf, r)]; s[r] = (lsel && KKOF(hf, r) <= db) ? ex2(x) : 0.f; }
; #pragma unroll
;                             for (int r = 0; r < 8; ++r) pw[r] = pk2(s[2 * r], s[2 * r + 1]);
.LBB0_578:
	s_andn2_b64 vcc, exec, s[14:15]
	s_cbranch_vccnz .LBB0_553
	ds_read2_b32 v[220:221], v16 offset0:35 offset1:36
	ds_read2_b32 v[222:223], v16 offset0:33 offset1:34
	ds_read2_b32 v[224:225], v16 offset0:27 offset1:28
	ds_read2_b32 v[226:227], v16 offset0:25 offset1:26
	ds_read2_b32 v[228:229], v16 offset0:19 offset1:20
	ds_read2_b32 v[230:231], v16 offset0:17 offset1:18
	ds_read2_b32 v[232:233], v16 offset0:11 offset1:12
	ds_read2_b32 v[234:235], v16 offset0:9 offset1:10
	v_cndmask_b32_e64 v236, v2, -1, s[22:23]
	s_waitcnt lgkmcnt(11)
	v_mfma_f32_32x32x16_bf16 v[100:115], v[4:7], v[148:151], v[84:99]
	s_waitcnt lgkmcnt(10)
	v_mfma_f32_32x32x16_bf16 v[100:115], v[8:11], v[152:155], v[100:115]
	s_waitcnt lgkmcnt(9)
	v_mfma_f32_32x32x16_bf16 v[100:115], v[12:15], v[156:159], v[100:115]
	s_waitcnt lgkmcnt(8)
	v_mfma_f32_32x32x16_bf16 v[100:115], v[116:119], v[160:163], v[100:115]
	s_waitcnt lgkmcnt(0)
	s_nop 10
	v_add_f32_e32 v100, v100, v221
	v_exp_f32_e32 v100, v100
	v_cmp_gt_i32_e32 vcc, 32, v236
	v_add_f32_e32 v101, v101, v220
	v_exp_f32_e32 v101, v101
	v_cndmask_b32_e64 v100, v100, 0, vcc
	v_cmp_gt_i32_e32 vcc, 33, v236
	v_add_f32_e32 v102, v102, v223
	v_exp_f32_e32 v102, v102
	v_cndmask_b32_e64 v101, v101, 0, vcc
	v_cmp_gt_i32_e32 vcc, 34, v236
	v_add_f32_e32 v103, v103, v222
	v_exp_f32_e32 v103, v103
	v_cndmask_b32_e64 v102, v102, 0, vcc
	v_cmp_gt_i32_e32 vcc, 35, v236
	v_add_f32_e32 v104, v104, v225
	v_exp_f32_e32 v104, v104
	v_cndmask_b32_e64 v103, v103, 0, vcc
	v_cmp_gt_i32_e32 vcc, 40, v236
	v_add_f32_e32 v105, v105, v224
	v_exp_f32_e32 v105, v105
	v_cndmask_b32_e64 v104, v104, 0, vcc
	v_cmp_gt_i32_e32 vcc, 41, v236
	v_add_f32_e32 v106, v106, v227
	v_exp_f32_e32 v106, v106
	v_cndmask_b32_e64 v105, v105, 0, vcc
	v_cmp_gt_i32_e32 vcc, 42, v236
	v_add_f32_e32 v107, v107, v226
	v_exp_f32_e32 v107, v107
	v_cndmask_b32_e64 v106, v106, 0, vcc
	v_cmp_gt_i32_e32 vcc, 43, v236
	v_add_f32_e32 v108, v108, v229
	v_exp_f32_e32 v108, v108
	v_cndmask_b32_e64 v107, v107, 0, vcc
	v_cmp_gt_i32_e32 vcc, 48, v236
	v_add_f32_e32 v109, v109, v228
	v_exp_f32_e32 v109, v109
	v_cndmask_b32_e64 v108, v108, 0, vcc
	v_cmp_gt_i32_e32 vcc, 49, v236
	v_add_f32_e32 v110, v110, v231
	v_exp_f32_e32 v110, v110
	v_cndmask_b32_e64 v109, v109, 0, vcc
	v_cmp_gt_i32_e32 vcc, 50, v236
	v_add_f32_e32 v111, v111, v230
	v_exp_f32_e32 v111, v111
	v_cndmask_b32_e64 v110, v110, 0, vcc
	v_cmp_gt_i32_e32 vcc, 51, v236
	v_add_f32_e32 v112, v112, v233
	v_exp_f32_e32 v112, v112
	v_cndmask_b32_e64 v111, v111, 0, vcc
	v_cmp_gt_i32_e32 vcc, 56, v236
	v_add_f32_e32 v113, v113, v232
	v_exp_f32_e32 v113, v113
	v_cndmask_b32_e64 v112, v112, 0, vcc
	v_cmp_gt_i32_e32 vcc, 57, v236
	v_add_f32_e32 v114, v114, v235
	v_exp_f32_e32 v114, v114
	v_cndmask_b32_e64 v113, v113, 0, vcc
	v_cmp_gt_i32_e32 vcc, 58, v236
	v_add_f32_e32 v115, v115, v234
	v_exp_f32_e32 v115, v115
	v_cndmask_b32_e64 v114, v114, 0, vcc
	v_cmp_gt_i32_e32 vcc, 59, v236
	s_nop 1
	v_cndmask_b32_e64 v115, v115, 0, vcc
	v_cvt_pk_bf16_f32 v220, v100, v101
	v_cvt_pk_bf16_f32 v221, v102, v103
	v_cvt_pk_bf16_f32 v222, v104, v105
	v_cvt_pk_bf16_f32 v223, v106, v107
	v_cvt_pk_bf16_f32 v100, v108, v109
	v_cvt_pk_bf16_f32 v101, v110, v111
	v_cvt_pk_bf16_f32 v102, v112, v113
	v_cvt_pk_bf16_f32 v103, v114, v115
	v_mov_b32_e32 v104, v220
	v_mov_b32_e32 v105, v221
	v_mov_b32_e32 v106, v222
	v_mov_b32_e32 v107, v223
	s_branch .LBB0_553

; __global__ void __launch_bounds__(NWAVES * 64, 2) fwd_megakernel(Params p) {
	.amdhsa_kernel _Z14fwd_megakernel6Params
		.amdhsa_group_segment_fixed_size 0
		.amdhsa_private_segment_fixed_size 0
		.amdhsa_kernarg_size 432
		.amdhsa_user_sgpr_count 2
		.amdhsa_user_sgpr_dispatch_ptr 0
		.amdhsa_user_sgpr_queue_ptr 0
		.amdhsa_user_sgpr_kernarg_segment_ptr 1
		.amdhsa_user_sgpr_dispatch_id 0
		.amdhsa_user_sgpr_kernarg_preload_length 0
		.amdhsa_user_sgpr_kernarg_preload_offset 0
		.amdhsa_user_sgpr_private_segment_size 0
		.amdhsa_uses_dynamic_stack 0
		.amdhsa_enable_private_segment 0
		.amdhsa_system_sgpr_workgroup_id_x 1
		.amdhsa_system_sgpr_workgroup_id_y 0
		.amdhsa_system_sgpr_workgroup_id_z 0
		.amdhsa_system_sgpr_workgroup_info 0
		.amdhsa_system_vgpr_workitem_id 2
		.amdhsa_next_free_vgpr 256
		.amdhsa_next_free_sgpr 102
		.amdhsa_accum_offset 256
		.amdhsa_reserve_vcc 1
		.amdhsa_float_round_mode_32 0
		.amdhsa_float_round_mode_16_64 0
		.amdhsa_float_denorm_mode_32 3
		.amdhsa_float_denorm_mode_16_64 3
		.amdhsa_dx10_clamp 1
		.amdhsa_ieee_mode 1
		.amdhsa_fp16_overflow 0
		.amdhsa_tg_split 0
		.amdhsa_exception_fp_ieee_invalid_op 0
		.amdhsa_exception_fp_denorm_src 0
		.amdhsa_exception_fp_ieee_div_zero 0
		.amdhsa_exception_fp_ieee_overflow 0
		.amdhsa_exception_fp_ieee_underflow 0
		.amdhsa_exception_fp_ieee_inexact 0
		.amdhsa_exception_int_div_zero 0
	.end_amdhsa_kernel

; __global__ void __launch_bounds__(NWAVES * 64, 2) fwd_megakernel(Params p) {
amdhsa.kernels:
  - .agpr_count:     0
    .args:
      - .offset:         0
        .size:           176
        .value_kind:     by_value
      - .offset:         176
        .size:           4
        .value_kind:     hidden_block_count_x
      - .offset:         180
        .size:           4
        .value_kind:     hidden_block_count_y
      - .offset:         184
        .size:           4
        .value_kind:     hidden_block_count_z
      - .offset:         188
        .size:           2
        .value_kind:     hidden_group_size_x
      - .offset:         190
        .size:           2
        .value_kind:     hidden_group_size_y
      - .offset:         192
        .size:           2
        .value_kind:     hidden_group_size_z
      - .offset:         194
        .size:           2
        .value_kind:     hidden_remainder_x
      - .offset:         196
        .size:           2
        .value_kind:     hidden_remainder_y
      - .offset:         198
        .size:           2
        .value_kind:     hidden_remainder_z
      - .offset:         216
        .size:           8
        .value_kind:     hidden_global_offset_x
      - .offset:         224
        .size:           8
        .value_kind:     hidden_global_offset_y
      - .offset:         232
        .size:           8
        .value_kind:     hidden_global_offset_z
      - .offset:         240
        .size:           2
        .value_kind:     hidden_grid_dims
      - .offset:         264
        .size:           8
        .value_kind:     hidden_multigrid_sync_arg
      - .offset:         296
        .size:           4
        .value_kind:     hidden_dynamic_lds_size
    .group_segment_fixed_size: 0
    .kernarg_segment_align: 8
    .kernarg_segment_size: 432
    .language:       OpenCL C
    .language_version:
      - 2
      - 0
    .max_flat_workgroup_size: 512
    .name:           _Z14fwd_megakernel6Params
    .private_segment_fixed_size: 0
    .sgpr_count:     108
    .sgpr_spill_count: 125
    .symbol:         _Z14fwd_megakernel6Params.kd
    .uniform_work_group_size: 1
    .uses_dynamic_stack: false
    .vgpr_count:     256
    .vgpr_spill_count: 0
    .wavefront_size: 64
